# v28 + P3 fused epilogue: ring re-loads of row groups 3..5 hoisted above the write-through stores, vmcnt re-derived
# speedup vs baseline: 1.0136x; 1.0136x over previous
.LBB0_564:
	s_lshl_b32 s2, s21, 5
	s_lshl_b32 s3, s18, 8
	s_or_b32 s2, s3, s2
	s_lshl_b32 s20, s20, 8
	v_and_or_b32 v162, v187, 24, s2
	s_add_i32 s2, s20, s19
	v_or_b32_e32 v164, s2, v189
	v_ashrrev_i32_e32 v165, 31, v164
	v_ashrrev_i32_e32 v163, 31, v162
	v_lshlrev_b64 v[130:131], 12, v[164:165]
	v_lshl_add_u64 v[130:131], s[76:77], 0, v[130:131]
	v_lshlrev_b64 v[132:133], 2, v[162:163]
	v_lshl_add_u64 v[130:131], v[130:131], 0, v[132:133]
	v_add_u32_e32 v169, s20, v168
	s_barrier
	v_mov_b64_e32 v[244:245], v[130:131]
	global_load_dwordx4 v[170:173], v[130:131], off nt
	global_load_dwordx4 v[174:177], v[130:131], off offset:16 nt
	global_load_dwordx4 v[178:181], v[130:131], off offset:512 nt
	global_load_dwordx4 v[182:185], v[130:131], off offset:528 nt
	v_or_b32_e32 v130, 32, v169
	v_or_b32_e32 v166, 16, v164
	v_ashrrev_i32_e32 v131, 31, v130
	v_ashrrev_i32_e32 v167, 31, v166
	v_lshlrev_b64 v[130:131], 12, v[130:131]
	v_lshlrev_b64 v[134:135], 12, v[166:167]
	v_lshl_add_u64 v[130:131], s[76:77], 0, v[130:131]
	v_lshl_add_u64 v[134:135], s[76:77], 0, v[134:135]
	v_lshl_add_u64 v[138:139], v[130:131], 0, v[132:133]
	v_lshl_add_u64 v[154:155], v[134:135], 0, v[132:133]
	global_load_dwordx4 v[134:137], v[138:139], off offset:16 nt
	global_load_dwordx4 v[142:145], v[138:139], off nt
	global_load_dwordx4 v[130:133], v[138:139], off offset:528 nt
	s_nop 0
	global_load_dwordx4 v[138:141], v[138:139], off offset:512 nt
	s_nop 0
	global_load_dwordx4 v[150:153], v[154:155], off offset:16 nt
	global_load_dwordx4 v[158:161], v[154:155], off nt
	global_load_dwordx4 v[146:149], v[154:155], off offset:528 nt
	s_nop 0
	global_load_dwordx4 v[154:157], v[154:155], off offset:512 nt
	s_mov_b64 s[98:99], 0x30000
	s_mov_b64 s[100:101], 0x50000
	v_lshl_add_u64 v[244:245], v[244:245], 0, s[98:99]
	global_load_dwordx4 v[196:199], v[244:245], off nt
	global_load_dwordx4 v[200:203], v[244:245], off offset:16 nt
	global_load_dwordx4 v[204:207], v[244:245], off offset:512 nt
	global_load_dwordx4 v[208:211], v[244:245], off offset:528 nt
	v_lshl_add_u64 v[244:245], v[244:245], 0, s[100:101]
	global_load_dwordx4 v[212:215], v[244:245], off nt
	global_load_dwordx4 v[216:219], v[244:245], off offset:16 nt
	global_load_dwordx4 v[220:223], v[244:245], off offset:512 nt
	global_load_dwordx4 v[224:227], v[244:245], off offset:528 nt
	s_mov_b64 s[98:99], 0x10000
	v_lshl_add_u64 v[244:245], v[244:245], 0, s[98:99]
	global_load_dwordx4 v[228:231], v[244:245], off nt
	global_load_dwordx4 v[232:235], v[244:245], off offset:16 nt
	global_load_dwordx4 v[236:239], v[244:245], off offset:512 nt
	global_load_dwordx4 v[240:243], v[244:245], off offset:528 nt
	v_lshlrev_b64 v[192:193], 11, v[164:165]
	v_lshl_add_u64 v[192:193], s[8:9], 0, v[192:193]
	s_mov_b64 s[2:3], 0x100
	v_lshl_add_u64 v[192:193], v[162:163], 1, v[192:193]
	v_lshl_add_u64 v[194:195], v[192:193], 0, s[2:3]
	s_lshl_b32 s4, s21, 2
	s_add_i32 s21, s4, 0
	v_cmp_gt_u32_e32 vcc, 16, v190
	s_waitcnt vmcnt(23)
	v_pk_add_f32 v[128:129], v[128:129], v[172:173]
	v_pk_add_f32 v[126:127], v[126:127], v[170:171]
	s_waitcnt vmcnt(22)
	v_pk_add_f32 v[124:125], v[124:125], v[176:177]
	v_pk_add_f32 v[122:123], v[122:123], v[174:175]
	s_waitcnt vmcnt(21)
	v_pk_add_f32 v[120:121], v[120:121], v[180:181]
	v_pk_add_f32 v[118:119], v[118:119], v[178:179]
	s_waitcnt vmcnt(20)
	v_pk_add_f32 v[170:171], v[116:117], v[184:185]
	v_pk_add_f32 v[172:173], v[114:115], v[182:183]
	v_cvt_pk_bf16_f32 v114, v126, v127
	v_cvt_pk_bf16_f32 v115, v128, v129
	v_cvt_pk_bf16_f32 v116, v122, v123
	v_cvt_pk_bf16_f32 v117, v124, v125
	v_mul_f32_e32 v127, v127, v127
	v_mul_f32_e32 v129, v129, v129
	v_mul_f32_e32 v123, v123, v123
	v_mul_f32_e32 v125, v125, v125
	v_mul_f32_e32 v165, v119, v119
	v_mul_f32_e32 v174, v121, v121
	v_mul_f32_e32 v175, v173, v173
	v_mul_f32_e32 v176, v171, v171
	global_store_dwordx4 v[192:193], v[114:117], off sc1
	s_nop 1
	v_fmac_f32_e32 v127, v126, v126
	v_fmac_f32_e32 v129, v128, v128
	v_fmac_f32_e32 v123, v122, v122
	v_fmac_f32_e32 v125, v124, v124
	v_cvt_pk_bf16_f32 v114, v118, v119
	v_cvt_pk_bf16_f32 v115, v120, v121
	v_fmac_f32_e32 v165, v118, v118
	v_fmac_f32_e32 v174, v120, v120
	v_fmac_f32_e32 v175, v172, v172
	v_fmac_f32_e32 v176, v170, v170
	v_cvt_pk_bf16_f32 v116, v172, v173
	v_cvt_pk_bf16_f32 v117, v170, v171
	v_add_f32_e32 v118, v127, v129
	v_add_f32_e32 v119, v123, v125
	global_store_dwordx4 v[194:195], v[114:117], off sc1
	s_nop 1
	v_add_f32_e32 v114, v165, v174
	v_add_f32_e32 v115, v175, v176
	v_add_f32_e32 v116, v118, v119
	v_add_f32_e32 v114, v114, v115
	v_add_f32_e32 v114, v116, v114
	v_mov_b32_e32 v115, v114
	s_nop 1
	v_permlane16_swap_b32_e32 v114, v115
	v_add_f32_e32 v114, v114, v115
	v_mov_b32_e32 v115, v114
	s_nop 1
	v_permlane32_swap_b32_e32 v114, v115
	v_lshl_add_u32 v165, v168, 4, s21
	s_and_saveexec_b64 s[4:5], vcc
	v_add_f32_e32 v114, v114, v115
	ds_write_b32 v165, v114
	s_or_b64 exec, exec, s[4:5]
	v_or_b32_e32 v114, 48, v169
	v_ashrrev_i32_e32 v115, 31, v114
	v_lshlrev_b64 v[114:115], 12, v[114:115]
	v_lshl_add_u64 v[114:115], s[76:77], 0, v[114:115]
	v_lshl_add_u64 v[122:123], v[162:163], 2, v[114:115]
	s_nop 0
	s_waitcnt vmcnt(15)
	v_pk_add_f32 v[146:147], v[98:99], v[146:147]
	v_lshlrev_b64 v[98:99], 11, v[166:167]
	v_lshl_add_u64 v[98:99], s[8:9], 0, v[98:99]
	v_pk_add_f32 v[112:113], v[112:113], v[160:161]
	v_pk_add_f32 v[110:111], v[110:111], v[158:159]
	v_pk_add_f32 v[106:107], v[106:107], v[150:151]
	v_lshl_add_u64 v[150:151], v[162:163], 1, v[98:99]
	v_cvt_pk_bf16_f32 v98, v110, v111
	v_cvt_pk_bf16_f32 v99, v112, v113
	v_pk_add_f32 v[108:109], v[108:109], v[152:153]
	v_pk_add_f32 v[148:149], v[100:101], v[148:149]
	v_cvt_pk_bf16_f32 v100, v106, v107
	v_cvt_pk_bf16_f32 v101, v108, v109
	s_waitcnt vmcnt(14)
	v_pk_add_f32 v[104:105], v[104:105], v[156:157]
	global_store_dwordx4 v[150:151], v[98:101], off sc1
	s_nop 1
	v_mul_f32_e32 v98, v111, v111
	v_mul_f32_e32 v99, v113, v113
	v_fmac_f32_e32 v98, v110, v110
	v_fmac_f32_e32 v99, v112, v112
	v_add_f32_e32 v98, v98, v99
	v_mul_f32_e32 v99, v107, v107
	v_mul_f32_e32 v100, v109, v109
	v_fmac_f32_e32 v99, v106, v106
	v_fmac_f32_e32 v100, v108, v108
	v_add_f32_e32 v99, v99, v100
	v_pk_add_f32 v[102:103], v[102:103], v[154:155]
	v_add_f32_e32 v108, v98, v99
	v_cvt_pk_bf16_f32 v98, v102, v103
	v_cvt_pk_bf16_f32 v99, v104, v105
	v_lshl_add_u64 v[106:107], v[150:151], 0, s[2:3]
	v_cvt_pk_bf16_f32 v100, v146, v147
	v_cvt_pk_bf16_f32 v101, v148, v149
	s_nop 0
	global_store_dwordx4 v[106:107], v[98:101], off sc1
	s_nop 1
	v_mul_f32_e32 v98, v103, v103
	v_mul_f32_e32 v99, v105, v105
	v_fmac_f32_e32 v98, v102, v102
	v_fmac_f32_e32 v99, v104, v104
	v_add_f32_e32 v98, v98, v99
	v_mul_f32_e32 v99, v147, v147
	v_mul_f32_e32 v100, v149, v149
	v_fmac_f32_e32 v99, v146, v146
	v_fmac_f32_e32 v100, v148, v148
	v_add_f32_e32 v99, v99, v100
	v_add_f32_e32 v98, v98, v99
	v_add_f32_e32 v98, v108, v98
	v_mov_b32_e32 v99, v98
	s_nop 1
	v_permlane16_swap_b32_e32 v98, v99
	v_add_f32_e32 v98, v98, v99
	v_mov_b32_e32 v99, v98
	s_nop 1
	v_permlane32_swap_b32_e32 v98, v99
	s_and_saveexec_b64 s[2:3], vcc
	v_add_f32_e32 v98, v98, v99
	ds_write_b32 v165, v98 offset:256
	s_or_b64 exec, exec, s[2:3]
	v_add_u32_e32 v98, 0x80, v169
	v_ashrrev_i32_e32 v99, 31, v98
	v_lshlrev_b64 v[98:99], 12, v[98:99]
	v_lshl_add_u64 v[98:99], s[76:77], 0, v[98:99]
	v_lshl_add_u64 v[106:107], v[162:163], 2, v[98:99]
	s_nop 0
	v_pk_add_f32 v[130:131], v[82:83], v[130:131]
	v_or_b32_e32 v82, 32, v164
	v_ashrrev_i32_e32 v83, 31, v82
	v_lshlrev_b64 v[82:83], 11, v[82:83]
	v_lshl_add_u64 v[82:83], s[8:9], 0, v[82:83]
	v_pk_add_f32 v[96:97], v[96:97], v[144:145]
	v_pk_add_f32 v[94:95], v[94:95], v[142:143]
	v_pk_add_f32 v[90:91], v[90:91], v[134:135]
	v_lshl_add_u64 v[134:135], v[162:163], 1, v[82:83]
	v_cvt_pk_bf16_f32 v82, v94, v95
	v_cvt_pk_bf16_f32 v83, v96, v97
	v_pk_add_f32 v[92:93], v[92:93], v[136:137]
	v_pk_add_f32 v[132:133], v[84:85], v[132:133]
	v_cvt_pk_bf16_f32 v84, v90, v91
	v_cvt_pk_bf16_f32 v85, v92, v93
	v_pk_add_f32 v[88:89], v[88:89], v[140:141]
	global_store_dwordx4 v[134:135], v[82:85], off sc1
	s_nop 1
	v_mul_f32_e32 v82, v95, v95
	v_mul_f32_e32 v83, v97, v97
	v_fmac_f32_e32 v82, v94, v94
	v_fmac_f32_e32 v83, v96, v96
	v_add_f32_e32 v82, v82, v83
	v_mul_f32_e32 v83, v91, v91
	v_mul_f32_e32 v84, v93, v93
	v_fmac_f32_e32 v83, v90, v90
	v_fmac_f32_e32 v84, v92, v92
	v_add_f32_e32 v83, v83, v84
	v_pk_add_f32 v[86:87], v[86:87], v[138:139]
	v_add_f32_e32 v92, v82, v83
	s_mov_b64 s[2:3], 0x100
	v_cvt_pk_bf16_f32 v82, v86, v87
	v_cvt_pk_bf16_f32 v83, v88, v89
	v_lshl_add_u64 v[90:91], v[134:135], 0, s[2:3]
	v_cvt_pk_bf16_f32 v84, v130, v131
	v_cvt_pk_bf16_f32 v85, v132, v133
	s_nop 0
	global_store_dwordx4 v[90:91], v[82:85], off sc1
	s_nop 1
	v_mul_f32_e32 v82, v87, v87
	v_mul_f32_e32 v83, v89, v89
	v_fmac_f32_e32 v82, v86, v86
	v_fmac_f32_e32 v83, v88, v88
	v_add_f32_e32 v82, v82, v83
	v_mul_f32_e32 v83, v131, v131
	v_mul_f32_e32 v84, v133, v133
	v_fmac_f32_e32 v83, v130, v130
	v_fmac_f32_e32 v84, v132, v132
	v_add_f32_e32 v83, v83, v84
	v_add_f32_e32 v82, v82, v83
	v_add_f32_e32 v82, v92, v82
	v_mov_b32_e32 v83, v82
	s_nop 1
	v_permlane16_swap_b32_e32 v82, v83
	v_add_f32_e32 v82, v82, v83
	v_mov_b32_e32 v83, v82
	s_nop 1
	v_permlane32_swap_b32_e32 v82, v83
	s_and_saveexec_b64 s[4:5], vcc
	v_add_f32_e32 v82, v82, v83
	ds_write_b32 v165, v82 offset:512
	s_or_b64 exec, exec, s[4:5]
	v_add_u32_e32 v82, 0x90, v169
	v_ashrrev_i32_e32 v83, 31, v82
	v_lshlrev_b64 v[82:83], 12, v[82:83]
	v_lshl_add_u64 v[82:83], s[76:77], 0, v[82:83]
	v_lshl_add_u64 v[90:91], v[162:163], 2, v[82:83]
	s_nop 0
	s_waitcnt vmcnt(14)
	v_pk_add_f32 v[114:115], v[66:67], v[208:209]
	v_or_b32_e32 v66, 48, v164
	v_ashrrev_i32_e32 v67, 31, v66
	v_lshlrev_b64 v[66:67], 11, v[66:67]
	v_lshl_add_u64 v[66:67], s[8:9], 0, v[66:67]
	v_pk_add_f32 v[80:81], v[80:81], v[198:199]
	v_pk_add_f32 v[78:79], v[78:79], v[196:197]
	v_pk_add_f32 v[74:75], v[74:75], v[200:201]
	v_lshl_add_u64 v[118:119], v[162:163], 1, v[66:67]
	v_cvt_pk_bf16_f32 v66, v78, v79
	v_cvt_pk_bf16_f32 v67, v80, v81
	v_pk_add_f32 v[76:77], v[76:77], v[202:203]
	v_pk_add_f32 v[116:117], v[68:69], v[210:211]
	v_cvt_pk_bf16_f32 v68, v74, v75
	v_cvt_pk_bf16_f32 v69, v76, v77
	v_pk_add_f32 v[72:73], v[72:73], v[206:207]
	global_store_dwordx4 v[118:119], v[66:69], off sc1
	s_nop 1
	v_mul_f32_e32 v66, v79, v79
	v_mul_f32_e32 v67, v81, v81
	v_fmac_f32_e32 v66, v78, v78
	v_fmac_f32_e32 v67, v80, v80
	v_add_f32_e32 v66, v66, v67
	v_mul_f32_e32 v67, v75, v75
	v_mul_f32_e32 v68, v77, v77
	v_fmac_f32_e32 v67, v74, v74
	v_fmac_f32_e32 v68, v76, v76
	v_add_f32_e32 v67, v67, v68
	v_pk_add_f32 v[70:71], v[70:71], v[204:205]
	v_add_f32_e32 v76, v66, v67
	v_cvt_pk_bf16_f32 v66, v70, v71
	v_cvt_pk_bf16_f32 v67, v72, v73
	v_lshl_add_u64 v[74:75], v[118:119], 0, s[2:3]
	v_cvt_pk_bf16_f32 v68, v114, v115
	v_cvt_pk_bf16_f32 v69, v116, v117
	s_nop 0
	global_store_dwordx4 v[74:75], v[66:69], off sc1
	s_nop 1
	v_mul_f32_e32 v66, v71, v71
	v_mul_f32_e32 v67, v73, v73
	v_fmac_f32_e32 v66, v70, v70
	v_fmac_f32_e32 v67, v72, v72
	v_add_f32_e32 v66, v66, v67
	v_mul_f32_e32 v67, v115, v115
	v_mul_f32_e32 v68, v117, v117
	v_fmac_f32_e32 v67, v114, v114
	v_fmac_f32_e32 v68, v116, v116
	v_add_f32_e32 v67, v67, v68
	v_add_f32_e32 v66, v66, v67
	v_add_f32_e32 v66, v76, v66
	v_mov_b32_e32 v67, v66
	s_nop 1
	v_permlane16_swap_b32_e32 v66, v67
	v_add_f32_e32 v66, v66, v67
	v_mov_b32_e32 v67, v66
	s_nop 1
	v_permlane32_swap_b32_e32 v66, v67
	s_and_saveexec_b64 s[2:3], vcc
	v_add_f32_e32 v66, v66, v67
	ds_write_b32 v165, v66 offset:768
	s_or_b64 exec, exec, s[2:3]
	v_add_u32_e32 v66, 0xa0, v169
	v_ashrrev_i32_e32 v67, 31, v66
	v_lshlrev_b64 v[66:67], 12, v[66:67]
	v_lshl_add_u64 v[66:67], s[76:77], 0, v[66:67]
	v_lshl_add_u64 v[74:75], v[162:163], 2, v[66:67]
	global_load_dwordx4 v[70:73], v[74:75], off offset:16 nt
	global_load_dwordx4 v[66:69], v[74:75], off nt
	global_load_dwordx4 v[78:81], v[74:75], off offset:528 nt
	s_nop 0
	global_load_dwordx4 v[74:77], v[74:75], off offset:512 nt
	s_waitcnt vmcnt(18)
	v_pk_add_f32 v[58:59], v[58:59], v[216:217]
	s_waitcnt vmcnt(16)
	v_pk_add_f32 v[102:103], v[50:51], v[224:225]
	v_add_u32_e32 v98, 0x80, v164
	v_ashrrev_i32_e32 v99, 31, v98
	v_lshlrev_b64 v[50:51], 11, v[98:99]
	v_lshl_add_u64 v[50:51], s[8:9], 0, v[50:51]
	v_pk_add_f32 v[64:65], v[64:65], v[214:215]
	v_pk_add_f32 v[62:63], v[62:63], v[212:213]
	v_pk_add_f32 v[60:61], v[60:61], v[218:219]
	v_lshl_add_u64 v[104:105], v[162:163], 1, v[50:51]
	v_cvt_pk_bf16_f32 v50, v62, v63
	v_cvt_pk_bf16_f32 v51, v64, v65
	v_pk_add_f32 v[100:101], v[52:53], v[226:227]
	v_cvt_pk_bf16_f32 v52, v58, v59
	v_cvt_pk_bf16_f32 v53, v60, v61
	v_pk_add_f32 v[56:57], v[56:57], v[222:223]
	global_store_dwordx4 v[104:105], v[50:53], off sc1
	s_nop 1
	v_mul_f32_e32 v50, v63, v63
	v_mul_f32_e32 v51, v65, v65
	v_fmac_f32_e32 v50, v62, v62
	v_fmac_f32_e32 v51, v64, v64
	v_add_f32_e32 v50, v50, v51
	v_mul_f32_e32 v51, v59, v59
	v_mul_f32_e32 v52, v61, v61
	v_fmac_f32_e32 v51, v58, v58
	v_fmac_f32_e32 v52, v60, v60
	v_add_f32_e32 v51, v51, v52
	v_pk_add_f32 v[54:55], v[54:55], v[220:221]
	v_add_f32_e32 v60, v50, v51
	s_mov_b64 s[2:3], 0x100
	v_cvt_pk_bf16_f32 v50, v54, v55
	v_cvt_pk_bf16_f32 v51, v56, v57
	v_lshl_add_u64 v[58:59], v[104:105], 0, s[2:3]
	v_cvt_pk_bf16_f32 v52, v102, v103
	v_cvt_pk_bf16_f32 v53, v100, v101
	s_addk_i32 s19, 0x80
	global_store_dwordx4 v[58:59], v[50:53], off sc1
	s_nop 1
	v_mul_f32_e32 v50, v55, v55
	v_mul_f32_e32 v51, v57, v57
	v_fmac_f32_e32 v50, v54, v54
	v_fmac_f32_e32 v51, v56, v56
	v_add_f32_e32 v50, v50, v51
	v_mul_f32_e32 v51, v103, v103
	v_mul_f32_e32 v52, v101, v101
	v_fmac_f32_e32 v51, v102, v102
	v_fmac_f32_e32 v52, v100, v100
	v_add_f32_e32 v51, v51, v52
	v_add_f32_e32 v50, v50, v51
	v_add_f32_e32 v50, v60, v50
	v_mov_b32_e32 v51, v50
	s_nop 1
	v_permlane16_swap_b32_e32 v50, v51
	v_add_f32_e32 v50, v50, v51
	v_mov_b32_e32 v51, v50
	v_or_b32_e32 v52, s19, v189
	s_nop 0
	v_permlane32_swap_b32_e32 v50, v51
	v_lshl_add_u32 v99, v52, 4, s21
	s_and_saveexec_b64 s[4:5], vcc
	v_add_f32_e32 v50, v50, v51
	ds_write_b32 v99, v50
	s_or_b64 exec, exec, s[4:5]
	v_add_u32_e32 v50, 0xb0, v169
	v_ashrrev_i32_e32 v51, 31, v50
	v_lshlrev_b64 v[50:51], 12, v[50:51]
	v_lshl_add_u64 v[50:51], s[76:77], 0, v[50:51]
	v_lshl_add_u64 v[58:59], v[162:163], 2, v[50:51]
	global_load_dwordx4 v[54:57], v[58:59], off offset:16 nt
	global_load_dwordx4 v[50:53], v[58:59], off nt
	global_load_dwordx4 v[62:65], v[58:59], off offset:528 nt
	s_nop 0
	global_load_dwordx4 v[58:61], v[58:59], off offset:512 nt
	s_waitcnt vmcnt(18)
	v_pk_add_f32 v[82:83], v[34:35], v[240:241]
	v_or_b32_e32 v34, 16, v98
	v_ashrrev_i32_e32 v35, 31, v34
	v_lshlrev_b64 v[34:35], 11, v[34:35]
	v_lshl_add_u64 v[34:35], s[8:9], 0, v[34:35]
	v_pk_add_f32 v[48:49], v[48:49], v[230:231]
	v_pk_add_f32 v[46:47], v[46:47], v[228:229]
	v_pk_add_f32 v[42:43], v[42:43], v[232:233]
	v_lshl_add_u64 v[86:87], v[162:163], 1, v[34:35]
	v_cvt_pk_bf16_f32 v34, v46, v47
	v_cvt_pk_bf16_f32 v35, v48, v49
	v_pk_add_f32 v[44:45], v[44:45], v[234:235]
	v_pk_add_f32 v[84:85], v[36:37], v[242:243]
	v_cvt_pk_bf16_f32 v36, v42, v43
	v_cvt_pk_bf16_f32 v37, v44, v45
	v_pk_add_f32 v[40:41], v[40:41], v[238:239]
	global_store_dwordx4 v[86:87], v[34:37], off sc1
	s_nop 1
	v_mul_f32_e32 v34, v47, v47
	v_mul_f32_e32 v35, v49, v49
	v_fmac_f32_e32 v34, v46, v46
	v_fmac_f32_e32 v35, v48, v48
	v_add_f32_e32 v34, v34, v35
	v_mul_f32_e32 v35, v43, v43
	v_mul_f32_e32 v36, v45, v45
	v_fmac_f32_e32 v35, v42, v42
	v_fmac_f32_e32 v36, v44, v44
	v_add_f32_e32 v35, v35, v36
	v_pk_add_f32 v[38:39], v[38:39], v[236:237]
	v_add_f32_e32 v44, v34, v35
	v_cvt_pk_bf16_f32 v34, v38, v39
	v_cvt_pk_bf16_f32 v35, v40, v41
	v_lshl_add_u64 v[42:43], v[86:87], 0, s[2:3]
	v_cvt_pk_bf16_f32 v36, v82, v83
	v_cvt_pk_bf16_f32 v37, v84, v85
	s_nop 0
	global_store_dwordx4 v[42:43], v[34:37], off sc1
	s_nop 1
	v_mul_f32_e32 v34, v39, v39
	v_mul_f32_e32 v35, v41, v41
	v_fmac_f32_e32 v34, v38, v38
	v_fmac_f32_e32 v35, v40, v40
	v_add_f32_e32 v34, v34, v35
	v_mul_f32_e32 v35, v83, v83
	v_mul_f32_e32 v36, v85, v85
	v_fmac_f32_e32 v35, v82, v82
	v_fmac_f32_e32 v36, v84, v84
	v_add_f32_e32 v35, v35, v36
	v_add_f32_e32 v34, v34, v35
	v_add_f32_e32 v34, v44, v34
	v_mov_b32_e32 v35, v34
	s_nop 1
	v_permlane16_swap_b32_e32 v34, v35
	v_add_f32_e32 v34, v34, v35
	v_mov_b32_e32 v35, v34
	s_nop 1
	v_permlane32_swap_b32_e32 v34, v35
	s_and_saveexec_b64 s[2:3], vcc
	v_add_f32_e32 v34, v34, v35
	ds_write_b32 v99, v34 offset:256
	s_or_b64 exec, exec, s[2:3]
	s_waitcnt vmcnt(8)
	v_pk_add_f32 v[36:37], v[18:19], v[74:75]
	v_or_b32_e32 v18, 32, v98
	v_ashrrev_i32_e32 v19, 31, v18
	v_lshlrev_b64 v[18:19], 11, v[18:19]
	v_lshl_add_u64 v[18:19], s[8:9], 0, v[18:19]
	v_pk_add_f32 v[28:29], v[28:29], v[68:69]
	v_pk_add_f32 v[26:27], v[26:27], v[66:67]
	v_lshl_add_u64 v[38:39], v[162:163], 1, v[18:19]
	v_cvt_pk_bf16_f32 v18, v26, v27
	v_cvt_pk_bf16_f32 v19, v28, v29
	v_pk_add_f32 v[34:35], v[20:21], v[76:77]
	v_pk_add_f32 v[30:31], v[30:31], v[70:71]
	v_pk_add_f32 v[32:33], v[32:33], v[72:73]
	v_cvt_pk_bf16_f32 v20, v30, v31
	s_mov_b64 s[2:3], 0x100
	v_cvt_pk_bf16_f32 v21, v32, v33
	v_pk_add_f32 v[22:23], v[22:23], v[78:79]
	global_store_dwordx4 v[38:39], v[18:21], off sc1
	s_nop 1
	v_mul_f32_e32 v18, v27, v27
	v_mul_f32_e32 v19, v29, v29
	v_fmac_f32_e32 v18, v26, v26
	v_fmac_f32_e32 v19, v28, v28
	v_add_f32_e32 v18, v18, v19
	v_mul_f32_e32 v19, v31, v31
	v_mul_f32_e32 v20, v33, v33
	v_fmac_f32_e32 v19, v30, v30
	v_fmac_f32_e32 v20, v32, v32
	v_add_f32_e32 v19, v19, v20
	v_add_f32_e32 v28, v18, v19
	v_cvt_pk_bf16_f32 v18, v36, v37
	v_cvt_pk_bf16_f32 v19, v34, v35
	v_pk_add_f32 v[24:25], v[24:25], v[80:81]
	v_lshl_add_u64 v[26:27], v[38:39], 0, s[2:3]
	v_cvt_pk_bf16_f32 v20, v22, v23
	v_cvt_pk_bf16_f32 v21, v24, v25
	s_nop 0
	global_store_dwordx4 v[26:27], v[18:21], off sc1
	s_nop 1
	v_mul_f32_e32 v18, v37, v37
	v_mul_f32_e32 v19, v35, v35
	v_fmac_f32_e32 v18, v36, v36
	v_fmac_f32_e32 v19, v34, v34
	v_add_f32_e32 v18, v18, v19
	v_mul_f32_e32 v19, v23, v23
	v_mul_f32_e32 v20, v25, v25
	v_fmac_f32_e32 v19, v22, v22
	v_fmac_f32_e32 v20, v24, v24
	v_add_f32_e32 v19, v19, v20
	v_add_f32_e32 v18, v18, v19
	v_add_f32_e32 v18, v28, v18
	v_mov_b32_e32 v19, v18
	s_nop 1
	v_permlane16_swap_b32_e32 v18, v19
	v_add_f32_e32 v18, v18, v19
	v_mov_b32_e32 v19, v18
	s_nop 1
	v_permlane32_swap_b32_e32 v18, v19
	s_and_saveexec_b64 s[4:5], vcc
	v_add_f32_e32 v18, v18, v19
	ds_write_b32 v99, v18 offset:512
	s_or_b64 exec, exec, s[4:5]
	s_waitcnt vmcnt(5)
	v_pk_add_f32 v[18:19], v[2:3], v[62:63]
	v_or_b32_e32 v2, 48, v98
	v_ashrrev_i32_e32 v3, 31, v2
	v_lshlrev_b64 v[2:3], 11, v[2:3]
	v_lshl_add_u64 v[2:3], s[8:9], 0, v[2:3]
	v_pk_add_f32 v[12:13], v[12:13], v[52:53]
	v_pk_add_f32 v[10:11], v[10:11], v[50:51]
	v_lshl_add_u64 v[22:23], v[162:163], 1, v[2:3]
	v_cvt_pk_bf16_f32 v2, v10, v11
	v_cvt_pk_bf16_f32 v3, v12, v13
	v_pk_add_f32 v[20:21], v[4:5], v[64:65]
	v_pk_add_f32 v[14:15], v[14:15], v[54:55]
	v_pk_add_f32 v[16:17], v[16:17], v[56:57]
	v_cvt_pk_bf16_f32 v4, v14, v15
	s_waitcnt vmcnt(4)
	v_pk_add_f32 v[8:9], v[8:9], v[60:61]
	v_cvt_pk_bf16_f32 v5, v16, v17
	v_pk_add_f32 v[6:7], v[6:7], v[58:59]
	global_store_dwordx4 v[22:23], v[2:5], off sc1
	s_nop 1
	v_mul_f32_e32 v2, v11, v11
	v_mul_f32_e32 v3, v13, v13
	v_fmac_f32_e32 v2, v10, v10
	v_fmac_f32_e32 v3, v12, v12
	v_add_f32_e32 v2, v2, v3
	v_mul_f32_e32 v3, v15, v15
	v_mul_f32_e32 v4, v17, v17
	v_fmac_f32_e32 v3, v14, v14
	v_fmac_f32_e32 v4, v16, v16
	v_add_f32_e32 v3, v3, v4
	v_add_f32_e32 v12, v2, v3
	v_cvt_pk_bf16_f32 v2, v6, v7
	v_cvt_pk_bf16_f32 v3, v8, v9
	v_lshl_add_u64 v[10:11], v[22:23], 0, s[2:3]
	v_cvt_pk_bf16_f32 v4, v18, v19
	v_cvt_pk_bf16_f32 v5, v20, v21
	s_nop 0
	global_store_dwordx4 v[10:11], v[2:5], off sc1
	s_nop 1
	v_mul_f32_e32 v2, v7, v7
	v_mul_f32_e32 v3, v9, v9
	v_fmac_f32_e32 v2, v6, v6
	v_fmac_f32_e32 v3, v8, v8
	v_add_f32_e32 v2, v2, v3
	v_mul_f32_e32 v3, v19, v19
	v_mul_f32_e32 v4, v21, v21
	v_fmac_f32_e32 v3, v18, v18
	v_fmac_f32_e32 v4, v20, v20
	v_add_f32_e32 v3, v3, v4
	v_add_f32_e32 v2, v2, v3
	v_add_f32_e32 v2, v12, v2
	v_mov_b32_e32 v3, v2
	s_nop 1
	v_permlane16_swap_b32_e32 v2, v3
	v_add_f32_e32 v2, v2, v3
	v_mov_b32_e32 v3, v2
	s_nop 1
	v_permlane32_swap_b32_e32 v2, v3
	s_and_saveexec_b64 s[2:3], vcc
	v_add_f32_e32 v2, v2, v3
	ds_write_b32 v99, v2 offset:768
	s_or_b64 exec, exec, s[2:3]
	s_waitcnt lgkmcnt(0)
	s_barrier
	s_andn2_b32 s1, s1, 63
	v_or_b32_e32 v2, s1, v190
	s_movk_i32 s1, 0x100
	v_cmp_gt_i32_e32 vcc, s1, v2
	s_and_saveexec_b64 s[2:3], vcc
	s_cbranch_execz .LBB0_582
	v_lshl_add_u32 v3, v2, 4, 0
	ds_read_b128 v[4:7], v3
	v_add_u32_e32 v2, s20, v2
	v_ashrrev_i32_e32 v3, 31, v2
	v_lshl_add_u64 v[2:3], v[2:3], 4, s[16:17]
	s_ashr_i32 s19, s18, 31
	s_waitcnt lgkmcnt(0)
	v_mov_b32_e32 v8, v5
	v_mov_b32_e32 v9, v6
	v_mov_b32_e32 v5, v7
	v_pk_add_f32 v[4:5], v[8:9], v[4:5]
	v_lshl_add_u64 v[2:3], s[18:19], 2, v[2:3]
	v_pk_add_f32 v[4:5], v[4:5], v[4:5] op_sel:[0,1] op_sel_hi:[1,0]
	global_store_dword v[2:3], v4, off sc1
